# diff tile loop edge layout: rare blocks (tile skip, reference rescale) moved out of line so the common path falls through; 3 taken branches per iteration become 1
# speedup vs baseline: 1.0028x; 1.0021x over previous
.LBB0_475:
	s_cmp_le_i32 s4, s2
	s_cselect_b64 s[62:63], -1, 0
	s_cmp_gt_i32 s4, s2
	s_cbranch_scc1 .LBB0_478
	s_mov_b64 s[12:13], s[52:53]
	s_add_i32 s0, s12, 32
	v_mov_b32_e32 v0, 0x1c00
	v_mad_u64_u32 v[66:67], s[0:1], s0, v0, v[140:141]
	s_lshl_b64 s[0:1], s[52:53], 1
	global_load_dwordx4 v[114:117], v[144:145], off
	v_lshl_add_u64 v[68:69], v[138:139], 0, s[0:1]
	global_load_dwordx4 v[118:121], v[66:67], off
	global_load_dwordx4 v[122:125], v[68:69], off
	v_lshl_add_u64 v[66:67], v[142:143], 0, s[0:1]
	global_load_dwordx4 v[126:129], v[66:67], off
	v_cmp_le_i32_e32 vcc, s4, v157
	s_and_saveexec_b64 s[64:65], vcc
	s_cbranch_execz .LBB0_477

.LBB0_481:
	s_or_b64 exec, exec, s[0:1]
	s_nop 5
	v_max3_f32 v170, v82, v66, v83
	v_max3_f32 v170, v170, v67, v84
	v_max3_f32 v170, v170, v68, v85
	v_max3_f32 v170, v170, v69, v86
	v_cndmask_b32_e32 v0, 0, v149, vcc
	v_max3_f32 v170, v170, v70, v87
	s_mov_b32 s0, 0x41200000
	v_max3_f32 v170, v170, v71, v88
	s_nop 0
	v_max3_f32 v170, v170, v72, v89
	s_nop 0
	v_max3_f32 v170, v170, v73, v90
	s_nop 0
	v_max3_f32 v170, v170, v74, v91
	s_nop 0
	v_max3_f32 v170, v170, v75, v92
	s_nop 0
	v_max3_f32 v170, v170, v76, v93
	s_nop 0
	v_max3_f32 v170, v170, v77, v94
	s_nop 0
	v_max3_f32 v170, v170, v78, v95
	s_nop 0
	v_max3_f32 v170, v170, v79, v96
	s_nop 0
	v_max3_f32 v170, v170, v80, v97
	s_nop 0
	v_max_f32_e32 v170, v170, v81
	v_mov_b32_e32 v171, v170
	s_nop 1
	v_permlane32_swap_b32_e32 v171, v170
	v_max_f32_e32 v170, v170, v171
	v_add_f32_e32 v170, v0, v170
	v_sub_f32_e32 v171, v170, v150
	v_cmp_lt_f32_e32 vcc, s0, v171
	s_cbranch_vccnz .Ldf_rescale

.LBB0_484:
	s_andn2_b32 s0, 1, s4
	s_mul_i32 s0, s0, 0x8c00
	s_add_i32 s0, s0, 0
	v_add_u32_e32 v0, s0, v151
	s_waitcnt vmcnt(3)
	ds_write_b128 v0, v[114:117]
	s_waitcnt vmcnt(2)
	ds_write_b128 v0, v[118:121] offset:8704
	v_add_u32_e32 v0, s0, v152
	v_add_u32_e32 v66, 0x4000, v0
	v_add_u32_e32 v0, 0x6800, v0
	s_waitcnt vmcnt(1)
	ds_write2_b64 v66, v[122:123], v[124:125] offset0:128 offset1:130
	s_waitcnt vmcnt(0)
	ds_write2_b64 v0, v[126:127], v[128:129] offset1:2
	s_branch .LBB0_474
.LBB0_477:
	s_or_b64 exec, exec, s[64:65]
	s_andn2_b64 vcc, exec, s[62:63]
	s_cbranch_vccnz .LBB0_474
	s_branch .LBB0_484
.LBB0_478:
	v_cmp_le_i32_e32 vcc, s4, v157
	s_and_saveexec_b64 s[64:65], vcc
	s_cbranch_execz .LBB0_477
	s_branch .LBB0_479
.Ldf_rescale:
	v_max_f32_e32 v170, v170, v170
	v_max_f32_e32 v171, v150, v150
	v_max_f32_e32 v170, v171, v170
	v_sub_f32_e32 v150, v150, v170
	v_exp_f32_e32 v150, v150
	s_nop 0
	v_pk_mul_f32 v[64:65], v[64:65], v[150:151] op_sel_hi:[1,0]
	v_pk_mul_f32 v[62:63], v[62:63], v[150:151] op_sel_hi:[1,0]
	v_pk_mul_f32 v[60:61], v[60:61], v[150:151] op_sel_hi:[1,0]
	v_pk_mul_f32 v[58:59], v[58:59], v[150:151] op_sel_hi:[1,0]
	v_pk_mul_f32 v[56:57], v[56:57], v[150:151] op_sel_hi:[1,0]
	v_pk_mul_f32 v[54:55], v[54:55], v[150:151] op_sel_hi:[1,0]
	v_pk_mul_f32 v[52:53], v[52:53], v[150:151] op_sel_hi:[1,0]
	v_pk_mul_f32 v[50:51], v[50:51], v[150:151] op_sel_hi:[1,0]
	v_pk_mul_f32 v[48:49], v[48:49], v[150:151] op_sel_hi:[1,0]
	v_pk_mul_f32 v[46:47], v[46:47], v[150:151] op_sel_hi:[1,0]
	v_pk_mul_f32 v[44:45], v[44:45], v[150:151] op_sel_hi:[1,0]
	v_pk_mul_f32 v[42:43], v[42:43], v[150:151] op_sel_hi:[1,0]
	v_pk_mul_f32 v[40:41], v[40:41], v[150:151] op_sel_hi:[1,0]
	v_pk_mul_f32 v[38:39], v[38:39], v[150:151] op_sel_hi:[1,0]
	v_pk_mul_f32 v[36:37], v[36:37], v[150:151] op_sel_hi:[1,0]
	v_pk_mul_f32 v[34:35], v[34:35], v[150:151] op_sel_hi:[1,0]
	v_pk_mul_f32 v[32:33], v[32:33], v[150:151] op_sel_hi:[1,0]
	v_pk_mul_f32 v[30:31], v[30:31], v[150:151] op_sel_hi:[1,0]
	v_pk_mul_f32 v[28:29], v[28:29], v[150:151] op_sel_hi:[1,0]
	v_pk_mul_f32 v[26:27], v[26:27], v[150:151] op_sel_hi:[1,0]
	v_pk_mul_f32 v[24:25], v[24:25], v[150:151] op_sel_hi:[1,0]
	v_pk_mul_f32 v[22:23], v[22:23], v[150:151] op_sel_hi:[1,0]
	v_pk_mul_f32 v[20:21], v[20:21], v[150:151] op_sel_hi:[1,0]
	v_pk_mul_f32 v[18:19], v[18:19], v[150:151] op_sel_hi:[1,0]
	v_pk_mul_f32 v[16:17], v[16:17], v[150:151] op_sel_hi:[1,0]
	v_pk_mul_f32 v[14:15], v[14:15], v[150:151] op_sel_hi:[1,0]
	v_pk_mul_f32 v[12:13], v[12:13], v[150:151] op_sel_hi:[1,0]
	v_pk_mul_f32 v[10:11], v[10:11], v[150:151] op_sel_hi:[1,0]
	v_pk_mul_f32 v[8:9], v[8:9], v[150:151] op_sel_hi:[1,0]
	v_pk_mul_f32 v[6:7], v[6:7], v[150:151] op_sel_hi:[1,0]
	v_pk_mul_f32 v[4:5], v[4:5], v[150:151] op_sel_hi:[1,0]
	v_pk_mul_f32 v[2:3], v[2:3], v[150:151] op_sel_hi:[1,0]
	v_mul_f32_e32 v131, v131, v150
	v_mov_b32_e32 v150, v170
	s_branch .LBB0_483
